# scan loops (P3): per-chunk register image prefetched one step ahead into a single register set instead of two sets two steps ahead; loop-end register rotation removed
# baseline (speedup 1.0000x reference)
.LBB0_350:
	s_add_i32 s16, s28, 2
	s_and_b64 s[4:5], s[4:5], exec
	v_add_f32_e32 v24, v0, v24
	v_add_f32_e32 v0, v219, v0
	s_cselect_b32 s0, s16, 64
	s_add_i32 s0, s0, -1
	v_max_f32_e32 v219, v0, v24
	s_lshl_b64 s[4:5], s[0:1], 6
	v_sub_f32_e32 v0, v0, v219
	s_add_u32 s4, s4, s21
	v_mul_f32_e32 v0, 0x3fb8aa3b, v0
	s_addc_u32 s5, s5, 0
	v_exp_f32_e32 v158, v0
	v_sub_f32_e32 v0, v24, v219
	s_add_i32 s0, s0, s22
	v_mov_b32_e32 v25, s5
	v_or_b32_e32 v24, s4, v104
	v_lshl_add_u64 v[28:29], s[4:5], 0, v[106:107]
	s_lshl_b64 s[14:15], s[0:1], 14
	v_lshlrev_b64 v[24:25], 10, v[24:25]
	v_lshlrev_b64 v[28:29], 10, v[28:29]
	s_add_u32 s14, s11, s14
	v_lshl_add_u64 v[24:25], v[102:103], 0, v[24:25]
	v_lshl_add_u64 v[28:29], v[102:103], 0, v[28:29]
	s_addc_u32 s15, s20, s15
	v_lshlrev_b32_e32 v225, 1, v100
	global_load_dwordx4 v[24:27], v[24:25], off
	s_nop 0
	global_load_dwordx4 v[32:35], v225, s[14:15]
	s_nop 0
	global_load_dwordx4 v[28:31], v[28:29], off
	s_nop 0
	global_load_dwordx4 v[44:47], v206, s[14:15]
	ds_read_b128 v[54:57], v213 offset:63488
	s_lshl_b64 s[14:15], s[0:1], 13
	v_mov_b32_e32 v51, s5
	v_or_b32_e32 v50, s4, v184
	v_lshl_add_u64 v[48:49], v[112:113], 0, s[14:15]
	v_lshlrev_b64 v[50:51], 5, v[50:51]
	v_add_u32_e32 v224, v193, v194
	v_add_u32_e32 v222, v195, v194
	v_lshl_add_u64 v[58:59], s[6:7], 0, v[50:51]
	ds_read_b128 v[62:65], v224 offset:17408
	ds_read_b128 v[66:69], v213 offset:63552
	global_load_dwordx4 v[48:51], v[48:49], off
	s_nop 0
	global_load_dwordx2 v[118:119], v[58:59], off
	ds_read_b128 v[70:73], v224 offset:17472
	ds_read_b128 v[74:77], v222 offset:34816
	s_waitcnt lgkmcnt(3)
	v_mfma_f32_16x16x32_bf16 v[54:57], v[54:57], v[62:65], 0
	ds_read_b128 v[78:81], v212
	ds_read_b128 v[82:85], v222 offset:34880
	s_lshl_b32 s0, s28, 6
	v_mul_f32_e32 v0, 0x3fb8aa3b, v0
	s_waitcnt lgkmcnt(3)
	v_mfma_f32_16x16x32_bf16 v[54:57], v[66:69], v[70:73], v[54:57]
	ds_read_b128 v[66:69], v212 offset:64
	s_or_b32 s14, s0, 64
	v_exp_f32_e32 v160, v0
	s_waitcnt lgkmcnt(2)
	v_mfma_f32_16x16x32_bf16 v[56:59], v[74:77], v[78:81], 0
	ds_read_b128 v[74:77], v222 offset:34944
	ds_read_b128 v[86:89], v212 offset:128
	ds_read_b128 v[90:93], v212 offset:192
	v_add_lshl_u32 v0, s14, v187, 13
	s_waitcnt lgkmcnt(3)
	v_mfma_f32_16x16x32_bf16 v[56:59], v[82:85], v[66:69], v[56:59]
	ds_read_b128 v[82:85], v222 offset:35008
	v_lshl_add_u64 v[98:99], v[108:109], 0, v[0:1]
	v_add_co_u32_e32 v150, vcc, s24, v98
	s_waitcnt lgkmcnt(2)
	v_mfma_f32_16x16x32_bf16 v[56:59], v[74:77], v[86:89], v[56:59]
	ds_read_b128 v[74:77], v214 offset:45056
	v_add_u32_e32 v221, v197, v203
	v_addc_co_u32_e32 v151, vcc, 0, v99, vcc
	s_waitcnt lgkmcnt(1)
	v_mfma_f32_16x16x32_bf16 v[56:59], v[82:85], v[90:93], v[56:59]
	ds_read_b128 v[82:85], v214 offset:45120
	ds_read_b128 v[94:97], v221
	v_add_co_u32_e32 v152, vcc, s25, v98
	s_waitcnt lgkmcnt(2)
	v_mfma_f32_16x16x32_bf16 v[74:77], v[74:77], v[62:65], 0
	v_addc_co_u32_e32 v153, vcc, 0, v99, vcc
	s_nop 1
	v_add_co_u32_e32 v58, vcc, s26, v98
	s_waitcnt lgkmcnt(1)
	v_mfma_f32_16x16x32_bf16 v[74:77], v[82:85], v[70:73], v[74:77]
	v_addc_co_u32_e32 v59, vcc, 0, v99, vcc
	global_load_dwordx2 v[156:157], v[98:99], off
	global_load_dwordx2 v[154:155], v[150:151], off
	s_nop 0
	global_load_dwordx2 v[152:153], v[152:153], off
	s_nop 0
	global_load_dwordx2 v[150:151], v[58:59], off
	ds_read_b128 v[82:85], v221 offset:64
	ds_read_b128 v[170:173], v221 offset:128
	s_waitcnt lgkmcnt(2)
	v_mfma_f32_16x16x32_bf16 v[94:97], v[94:97], v[78:81], 0
	v_add_u32_e32 v0, s0, v205
	v_lshlrev_b64 v[58:59], 13, v[0:1]
	v_lshl_add_u64 v[58:59], v[110:111], 0, v[58:59]
	global_load_dwordx2 v[168:169], v[58:59], off
	global_load_dwordx2 v[166:167], v[58:59], off offset:32
	global_load_dwordx2 v[164:165], v[58:59], off offset:64
	global_load_dwordx2 v[162:163], v[58:59], off offset:96
	s_waitcnt lgkmcnt(1)
	v_mfma_f32_16x16x32_bf16 v[82:85], v[82:85], v[66:69], v[94:97]
	v_mov_b32_e32 v55, v56
	s_nop 1
	v_mul_f32_e32 v94, v56, v61
	ds_read_b128 v[56:59], v214 offset:47360
	ds_read_b128 v[174:177], v221 offset:192
	v_pk_fma_f32 v[54:55], v[54:55], v[60:61], v[94:95] op_sel_hi:[1,1,0]
	ds_read_b128 v[94:97], v214 offset:47424
	v_mul_f32_e32 v52, 0xbfb8aa3b, v52
	ds_bpermute_b32 v98, v196, v54
	v_exp_f32_e32 v99, v52
	ds_read_b128 v[52:55], v221 offset:4352
	s_waitcnt lgkmcnt(5)
	v_mfma_f32_16x16x32_bf16 v[82:85], v[170:173], v[86:89], v[82:85]
	ds_read_b128 v[170:173], v221 offset:4416
	v_mov_b32_e32 v230, v61
	s_waitcnt lgkmcnt(2)
	v_max_f32_e64 v98, |v98|, |v98|
	v_mfma_f32_16x16x32_bf16 v[56:59], v[56:59], v[62:65], 0
	v_max_f32_e32 v98, v98, v99
	v_rcp_f32_e32 v98, v98
	ds_read_b128 v[178:181], v221 offset:8768
	v_mfma_f32_16x16x32_bf16 v[82:85], v[174:177], v[90:93], v[82:85]
	v_add_u32_e32 v223, s27, v200
	v_mfma_f32_16x16x32_bf16 v[94:97], v[94:97], v[70:73], v[56:59]
	s_nop 2
	ds_read_b128 v[56:59], v221 offset:4480
	s_waitcnt lgkmcnt(3)
	v_mfma_f32_16x16x32_bf16 v[52:55], v[52:55], v[78:81], 0
	v_mul_f32_e64 v174, v230, v84
	v_mul_f32_e64 v175, v230, v85
	v_pk_mul_f32 v[176:177], v[230:231], v[82:83] op_sel_hi:[0,1]
	ds_read_b128 v[82:85], v221 offset:4544
	s_waitcnt lgkmcnt(3)
	v_mfma_f32_16x16x32_bf16 v[170:173], v[170:173], v[66:69], v[52:55]
	v_fma_f32 v174, v60, v76, v174
	v_fma_f32 v175, v60, v77, v175
	v_pk_fma_f32 v[176:177], v[60:61], v[74:75], v[176:177] op_sel_hi:[0,1,1]
	v_pk_mul_f32 v[176:177], v[98:99], v[176:177] op_sel_hi:[0,1]
	ds_read_b128 v[52:55], v214 offset:49664
	s_waitcnt lgkmcnt(2)
	v_mfma_f32_16x16x32_bf16 v[74:77], v[56:59], v[86:89], v[170:173]
	ds_read_b128 v[56:59], v214 offset:49728
	v_mul_f32_e32 v61, v176, v176
	v_add_f32_e32 v232, v176, v177
	s_waitcnt lgkmcnt(2)
	v_mfma_f32_16x16x32_bf16 v[74:77], v[82:85], v[90:93], v[74:77]
	ds_read_b128 v[82:85], v221 offset:8704
	v_pk_mul_f32 v[170:171], v[98:99], v[174:175] op_sel_hi:[0,1]
	v_mul_f32_e32 v231, v170, v170
	s_waitcnt lgkmcnt(2)
	v_mfma_f32_16x16x32_bf16 v[172:175], v[52:55], v[62:65], 0
	v_mul_f32_e32 v99, v177, v177
	s_nop 1
	v_pk_mul_f32 v[182:183], v[230:231], v[76:77] op_sel_hi:[0,1]
	v_pk_mul_f32 v[188:189], v[230:231], v[74:75] op_sel_hi:[0,1]
	s_waitcnt lgkmcnt(1)
	v_mfma_f32_16x16x32_bf16 v[226:229], v[56:59], v[70:73], v[172:175]
	ds_read_b128 v[74:77], v221 offset:8896
	v_mul_f32_e32 v237, v171, v171
	v_add_f32_e32 v234, v170, v171
	ds_read_b128 v[172:175], v221 offset:8832
	s_waitcnt lgkmcnt(2)
	v_mfma_f32_16x16x32_bf16 v[82:85], v[82:85], v[78:81], 0
	v_mfma_f32_16x16x32_bf16 v[82:85], v[178:181], v[66:69], v[82:85]
	v_fma_f32 v178, v60, v96, v182
	v_fma_f32 v179, v60, v97, v183
	v_pk_fma_f32 v[180:181], v[60:61], v[94:95], v[188:189] op_sel_hi:[0,1,1]
	ds_read_b128 v[94:97], v215 offset:45056
	s_waitcnt lgkmcnt(1)
	v_mfma_f32_16x16x32_bf16 v[82:85], v[172:175], v[86:89], v[82:85]
	v_mul_f32_e64 v174, v98, v178
	v_mul_f32_e64 v175, v98, v179
	v_pk_mul_f32 v[188:189], v[98:99], v[180:181] op_sel_hi:[0,1]
	ds_read_b128 v[178:181], v215 offset:45120
	v_mfma_f32_16x16x32_bf16 v[74:77], v[74:77], v[90:93], v[82:85]
	v_mov_b32_e32 v236, v175
	v_mul_f32_e32 v233, v188, v188
	v_mul_f32_e32 v235, v189, v189
	ds_read_b128 v[82:85], v216
	s_waitcnt lgkmcnt(2)
	v_mfma_f32_16x16x32_bf16 v[62:65], v[94:97], v[62:65], 0
	v_mul_f32_e32 v94, v174, v174
	v_pk_fma_f32 v[238:239], v[174:175], v[174:175], v[94:95] op_sel_hi:[1,1,0]
	ds_read_b128 v[94:97], v216 offset:64
	s_waitcnt lgkmcnt(2)
	v_mfma_f32_16x16x32_bf16 v[62:65], v[178:181], v[70:73], v[62:65]
	ds_read_b128 v[70:73], v216 offset:128
	v_pk_mul_f32 v[172:173], v[230:231], v[76:77] op_sel_hi:[0,1]
	v_pk_mul_f32 v[178:179], v[230:231], v[74:75] op_sel_hi:[0,1]
	s_waitcnt lgkmcnt(2)
	v_mfma_f32_16x16x32_bf16 v[74:77], v[82:85], v[78:81], 0
	ds_read_b128 v[78:81], v216 offset:192
	v_pk_fma_f32 v[82:83], v[60:61], v[228:229], v[172:173] op_sel_hi:[0,1,1]
	v_pk_fma_f32 v[84:85], v[60:61], v[226:227], v[178:179] op_sel_hi:[0,1,1]
	s_waitcnt lgkmcnt(2)
	v_mfma_f32_16x16x32_bf16 v[66:69], v[94:97], v[66:69], v[74:77]
	v_mul_f32_e64 v178, v98, v82
	v_mul_f32_e64 v179, v98, v83
	v_pk_mul_f32 v[182:183], v[98:99], v[84:85] op_sel_hi:[0,1]
	v_mov_b32_e32 v238, v1
	s_waitcnt lgkmcnt(1)
	v_mfma_f32_16x16x32_bf16 v[66:69], v[70:73], v[86:89], v[66:69]
	v_mul_f32_e32 v75, v182, v182
	v_mul_f32_e32 v71, v183, v183
	v_mul_f32_e32 v73, v178, v178
	s_waitcnt lgkmcnt(0)
	v_mfma_f32_16x16x32_bf16 v[66:69], v[78:81], v[90:93], v[66:69]
	v_mul_f32_e32 v77, v179, v179
	v_mov_b32_e32 v74, v182
	v_mov_b32_e32 v70, v183
	v_mov_b32_e32 v72, v178
	v_mov_b32_e32 v76, v179
	s_nop 2
	v_pk_mul_f32 v[68:69], v[230:231], v[68:69] op_sel_hi:[0,1]
	v_pk_mul_f32 v[66:67], v[230:231], v[66:67] op_sel_hi:[0,1]
	v_pk_fma_f32 v[64:65], v[60:61], v[64:65], v[68:69] op_sel_hi:[0,1,1]
	v_pk_fma_f32 v[62:63], v[60:61], v[62:63], v[66:67] op_sel_hi:[0,1,1]
	v_pk_mul_f32 v[172:173], v[98:99], v[64:65] op_sel_hi:[0,1]
	v_pk_mul_f32 v[180:181], v[98:99], v[62:63] op_sel_hi:[0,1]
	v_mov_b32_e32 v60, v188
	v_mov_b32_e32 v98, v189
	v_mov_b32_e32 v230, v174
	v_pk_add_f32 v[60:61], v[60:61], v[98:99]
	v_pk_add_f32 v[78:79], v[230:231], v[236:237]
	v_mul_f32_e32 v63, v180, v180
	v_pk_add_f32 v[60:61], v[60:61], v[78:79]
	v_pk_add_f32 v[78:79], v[232:233], v[234:235]
	v_mul_f32_e32 v65, v181, v181
	v_mul_f32_e32 v67, v172, v172
	v_mul_f32_e32 v69, v173, v173
	v_pk_add_f32 v[78:79], v[78:79], v[238:239]
	v_pk_add_f32 v[70:71], v[74:75], v[70:71]
	v_pk_add_f32 v[72:73], v[72:73], v[76:77]
	v_mov_b32_e32 v62, v180
	v_mov_b32_e32 v64, v181
	v_mov_b32_e32 v66, v172
	v_mov_b32_e32 v68, v173
	v_pk_add_f32 v[60:61], v[60:61], v[78:79]
	v_pk_add_f32 v[70:71], v[70:71], v[72:73]
	v_pk_add_f32 v[62:63], v[62:63], v[64:65]
	v_pk_add_f32 v[64:65], v[66:67], v[68:69]
	v_pk_add_f32 v[60:61], v[60:61], v[70:71]
	v_pk_add_f32 v[62:63], v[62:63], v[64:65]
	s_nop 0
	v_pk_add_f32 v[60:61], v[60:61], v[62:63]
	ds_bpermute_b32 v62, v198, v60
	ds_bpermute_b32 v63, v198, v61
	s_waitcnt lgkmcnt(0)
	v_pk_add_f32 v[60:61], v[60:61], v[62:63]
	ds_bpermute_b32 v62, v199, v60
	ds_bpermute_b32 v63, v199, v61
	s_and_saveexec_b64 s[4:5], s[2:3]
	s_cbranch_execz .LBB0_352
	s_waitcnt lgkmcnt(0)
	v_pk_add_f32 v[52:53], v[60:61], v[62:63]
	ds_write_b64 v223, v[52:53]
	ds_read_b128 v[52:55], v214 offset:49664
	ds_read_b128 v[56:59], v214 offset:49728

.LBB0_358:
	ds_read_b128 v[52:55], v200
	ds_read_b128 v[56:59], v202
	v_lshlrev_b64 v[60:61], 11, v[0:1]
	s_waitcnt vmcnt(3)
	v_lshlrev_b32_e32 v62, 16, v168
	v_and_b32_e32 v63, 0xffff0000, v168
	s_waitcnt lgkmcnt(1)
	v_pk_add_f32 v[52:53], v[52:53], v[54:55]
	v_lshlrev_b32_e32 v54, 16, v169
	v_pk_mul_f32 v[64:65], v[52:53], s[10:11] op_sel_hi:[1,0]
	v_and_b32_e32 v55, 0xffff0000, v169
	v_fma_f32 v0, -v64, v64, v65
	v_max_f32_e32 v0, 0, v0
	v_add_f32_e32 v0, 0x3727c5ac, v0
	v_rsq_f32_e32 v0, v0
	v_pk_add_f32 v[52:53], v[176:177], v[64:65] op_sel_hi:[1,0] neg_lo:[0,1] neg_hi:[0,1]
	v_lshl_add_u64 v[60:61], v[116:117], 0, v[60:61]
	v_pk_mul_f32 v[52:53], v[52:53], v[62:63]
	v_pk_add_f32 v[66:67], v[174:175], v[64:65] op_sel_hi:[1,0] neg_lo:[0,1] neg_hi:[0,1]
	v_pk_mul_f32 v[52:53], v[52:53], v[0:1] op_sel_hi:[1,0]
	s_min_u32 s0, s28, 61
	s_waitcnt lgkmcnt(0)
	v_pk_mul_f32 v[52:53], v[56:57], v[52:53]
	v_pk_add_f32 v[56:57], v[170:171], v[64:65] op_sel_hi:[1,0] neg_lo:[0,1] neg_hi:[0,1]
	v_cvt_pk_bf16_f32 v52, v52, v53
	v_pk_mul_f32 v[54:55], v[56:57], v[54:55]
	s_waitcnt vmcnt(2)
	v_lshlrev_b32_e32 v56, 16, v166
	v_pk_mul_f32 v[54:55], v[54:55], v[0:1] op_sel_hi:[1,0]
	v_and_b32_e32 v57, 0xffff0000, v166
	v_pk_mul_f32 v[54:55], v[58:59], v[54:55]
	v_pk_add_f32 v[58:59], v[188:189], v[64:65] op_sel_hi:[1,0] neg_lo:[0,1] neg_hi:[0,1]
	v_cvt_pk_bf16_f32 v53, v54, v55
	global_store_dwordx2 v[60:61], v[52:53], off offset:1024
	ds_read_b128 v[52:55], v202 offset:64
	v_pk_mul_f32 v[56:57], v[58:59], v[56:57]
	s_add_i32 s15, s0, 2
	v_pk_mul_f32 v[62:63], v[56:57], v[0:1] op_sel_hi:[1,0]
	ds_read_b128 v[56:59], v202 offset:128
	s_waitcnt lgkmcnt(1)
	v_pk_mul_f32 v[52:53], v[52:53], v[62:63]
	v_lshlrev_b32_e32 v62, 16, v167
	v_and_b32_e32 v63, 0xffff0000, v167
	v_pk_mul_f32 v[62:63], v[66:67], v[62:63]
	v_cvt_pk_bf16_f32 v52, v52, v53
	v_pk_mul_f32 v[62:63], v[62:63], v[0:1] op_sel_hi:[1,0]
	s_lshl_b32 s0, s15, 6
	v_pk_mul_f32 v[54:55], v[54:55], v[62:63]
	s_add_i32 s0, s0, s21
	v_cvt_pk_bf16_f32 v53, v54, v55
	global_store_dwordx2 v[60:61], v[52:53], off offset:1056
	s_waitcnt vmcnt(3)
	v_lshlrev_b32_e32 v52, 16, v164
	v_and_b32_e32 v53, 0xffff0000, v164
	v_pk_add_f32 v[54:55], v[182:183], v[64:65] op_sel_hi:[1,0] neg_lo:[0,1] neg_hi:[0,1]
	s_add_i32 s15, s15, s22
	v_pk_mul_f32 v[52:53], v[54:55], v[52:53]
	v_lshlrev_b32_e32 v54, 16, v165
	v_pk_mul_f32 v[52:53], v[52:53], v[0:1] op_sel_hi:[1,0]
	v_and_b32_e32 v55, 0xffff0000, v165
	s_waitcnt lgkmcnt(0)
	v_pk_mul_f32 v[52:53], v[56:57], v[52:53]
	v_pk_add_f32 v[56:57], v[178:179], v[64:65] op_sel_hi:[1,0] neg_lo:[0,1] neg_hi:[0,1]
	v_cvt_pk_bf16_f32 v52, v52, v53
	v_pk_mul_f32 v[54:55], v[56:57], v[54:55]
	s_waitcnt vmcnt(2)
	v_lshlrev_b32_e32 v56, 16, v162
	v_pk_mul_f32 v[54:55], v[54:55], v[0:1] op_sel_hi:[1,0]
	v_and_b32_e32 v57, 0xffff0000, v162
	v_pk_mul_f32 v[54:55], v[58:59], v[54:55]
	v_pk_add_f32 v[58:59], v[180:181], v[64:65] op_sel_hi:[1,0] neg_lo:[0,1] neg_hi:[0,1]
	v_cvt_pk_bf16_f32 v53, v54, v55
	global_store_dwordx2 v[60:61], v[52:53], off offset:1088
	ds_read_b128 v[52:55], v202 offset:192
	v_pk_mul_f32 v[56:57], v[58:59], v[56:57]
	v_pk_add_f32 v[58:59], v[172:173], v[64:65] op_sel_hi:[1,0] neg_lo:[0,1] neg_hi:[0,1]
	v_pk_mul_f32 v[56:57], v[56:57], v[0:1] op_sel_hi:[1,0]
	s_lshl_b32 s17, s15, 14
	s_waitcnt lgkmcnt(0)
	v_pk_mul_f32 v[52:53], v[52:53], v[56:57]
	v_lshlrev_b32_e32 v56, 16, v163
	v_and_b32_e32 v57, 0xffff0000, v163
	v_pk_mul_f32 v[56:57], v[58:59], v[56:57]
	v_cvt_pk_bf16_f32 v52, v52, v53
	v_pk_mul_f32 v[56:57], v[56:57], v[0:1] op_sel_hi:[1,0]
	v_lshlrev_b32_e32 v0, 16, v156
	v_pk_mul_f32 v[54:55], v[54:55], v[56:57]
	s_add_u32 s18, s11, s17
	v_cvt_pk_bf16_f32 v53, v54, v55
	global_store_dwordx2 v[60:61], v[52:53], off offset:1120
	ds_write_b128 v207, v[24:27]
	ds_write_b128 v208, v[32:35] offset:26624
	ds_write_b128 v209, v[28:31]
	ds_write_b128 v210, v[44:47] offset:26624
	ds_write_b128 v190, v[48:51] offset:17408
	v_and_b32_e32 v26, 0xffff0000, v156
	v_lshlrev_b32_e32 v24, 16, v154
	v_and_b32_e32 v27, 0xffff0000, v154
	v_lshlrev_b32_e32 v25, 16, v152
	v_and_b32_e32 v44, 0xffff0000, v152
	v_lshlrev_b32_e32 v47, 16, v150
	v_and_b32_e32 v32, 0xffff0000, v150
	v_lshlrev_b32_e32 v28, 16, v157
	v_and_b32_e32 v29, 0xffff0000, v157
	v_lshlrev_b32_e32 v30, 16, v155
	v_and_b32_e32 v31, 0xffff0000, v155
	v_lshlrev_b32_e32 v45, 16, v153
	v_and_b32_e32 v46, 0xffff0000, v153
	v_lshlrev_b32_e32 v33, 16, v151
	v_and_b32_e32 v34, 0xffff0000, v151
	v_cvt_pk_bf16_f32 v24, v0, v24
	v_cvt_pk_bf16_f32 v25, v25, v47
	v_cvt_pk_bf16_f32 v26, v26, v27
	v_cvt_pk_bf16_f32 v27, v44, v32
	ds_write2_b64 v220, v[24:25], v[26:27] offset1:18
	v_cvt_pk_bf16_f32 v24, v28, v30
	v_cvt_pk_bf16_f32 v25, v45, v33
	v_cvt_pk_bf16_f32 v26, v29, v31
	v_cvt_pk_bf16_f32 v27, v46, v34
	ds_write2_b64 v220, v[24:25], v[26:27] offset0:36 offset1:54
	v_add_f32_e32 v0, v118, v219
	v_add_f32_e32 v24, v119, v118
	v_max_f32_e32 v25, v0, v24
	v_sub_f32_e32 v24, v24, v25
	v_mul_f32_e32 v24, 0x3fb8aa3b, v24
	v_exp_f32_e32 v24, v24
	v_sub_f32_e32 v0, v0, v25
	ds_bpermute_b32 v174, v192, v25
	v_mov_b32_e32 v25, v105
	ds_bpermute_b32 v60, v192, v24
	v_or_b32_e32 v24, s0, v104
	v_lshl_add_u64 v[26:27], s[0:1], 0, v[106:107]
	v_lshlrev_b64 v[24:25], 10, v[24:25]
	v_lshlrev_b64 v[26:27], 10, v[26:27]
	v_lshl_add_u64 v[24:25], v[102:103], 0, v[24:25]
	v_lshl_add_u64 v[28:29], v[102:103], 0, v[26:27]
	s_waitcnt lgkmcnt(0)
	s_barrier
	s_addc_u32 s19, s20, 0
	global_load_dwordx4 v[24:27], v[24:25], off
	s_nop 0
	global_load_dwordx4 v[28:31], v[28:29], off
	s_nop 0
	global_load_dwordx4 v[32:35], v225, s[18:19]
	global_load_dwordx4 v[44:47], v206, s[18:19]
	ds_read_b128 v[52:55], v213 offset:63488
	ds_read_b128 v[62:65], v224 offset:17408
	ds_read_b128 v[56:59], v213 offset:63552
	v_or_b32_e32 v50, s0, v184
	v_mov_b32_e32 v51, v101
	s_lshl_b32 s18, s15, 13
	s_mov_b32 s19, s1
	v_lshlrev_b64 v[50:51], 5, v[50:51]
	v_lshl_add_u64 v[48:49], v[112:113], 0, s[18:19]
	v_lshl_add_u64 v[66:67], s[6:7], 0, v[50:51]
	ds_bpermute_b32 v76, v191, v118
	ds_bpermute_b32 v77, v191, v119
	global_load_dwordx4 v[48:51], v[48:49], off
	s_nop 0
	global_load_dwordx2 v[118:119], v[66:67], off
	ds_read_b128 v[66:69], v224 offset:17472
	ds_read_b128 v[70:73], v222 offset:34816
	s_waitcnt lgkmcnt(5)
	v_mfma_f32_16x16x32_bf16 v[52:55], v[52:55], v[62:65], 0
	ds_read_b128 v[78:81], v212
	ds_read_b128 v[82:85], v222 offset:34880
	ds_read_b128 v[86:89], v212 offset:64
	v_mul_f32_e32 v0, 0x3fb8aa3b, v0
	s_waitcnt lgkmcnt(4)
	v_mfma_f32_16x16x32_bf16 v[52:55], v[56:59], v[66:69], v[52:55]
	v_exp_f32_e32 v0, v0
	s_min_u32 s0, s28, 61
	s_lshl_b32 s0, s0, 18
	s_waitcnt lgkmcnt(2)
	v_mfma_f32_16x16x32_bf16 v[54:57], v[70:73], v[78:81], 0
	ds_read_b128 v[70:73], v222 offset:34944
	ds_read_b128 v[90:93], v212 offset:128
	ds_read_b128 v[94:97], v212 offset:192
	ds_bpermute_b32 v61, v192, v0
	s_waitcnt lgkmcnt(4)
	v_mfma_f32_16x16x32_bf16 v[54:57], v[82:85], v[86:89], v[54:57]
	ds_read_b128 v[82:85], v222 offset:35008
	v_add_lshl_u32 v0, v204, s0, 1
	v_lshl_add_u64 v[74:75], v[108:109], 0, v[0:1]
	s_waitcnt lgkmcnt(3)
	v_mfma_f32_16x16x32_bf16 v[54:57], v[70:73], v[90:93], v[54:57]
	ds_read_b128 v[70:73], v214 offset:45056
	v_add_co_u32_e32 v98, vcc, s24, v74
	s_waitcnt lgkmcnt(1)
	v_mfma_f32_16x16x32_bf16 v[54:57], v[82:85], v[94:97], v[54:57]
	v_addc_co_u32_e32 v99, vcc, 0, v75, vcc
	v_add_co_u32_e32 v152, vcc, s25, v74
	s_nop 5
	ds_read_b128 v[56:59], v214 offset:45120
	ds_read_b128 v[82:85], v221
	s_waitcnt lgkmcnt(2)
	v_mfma_f32_16x16x32_bf16 v[70:73], v[70:73], v[62:65], 0
	v_addc_co_u32_e32 v153, vcc, 0, v75, vcc
	v_add_co_u32_e32 v156, vcc, s26, v74
	s_waitcnt lgkmcnt(1)
	v_mfma_f32_16x16x32_bf16 v[56:59], v[56:59], v[66:69], v[70:73]
	v_addc_co_u32_e32 v157, vcc, 0, v75, vcc
	global_load_dwordx2 v[154:155], v[74:75], off
	global_load_dwordx2 v[150:151], v[98:99], off
	s_nop 0
	global_load_dwordx2 v[152:153], v[152:153], off
	s_nop 0
	global_load_dwordx2 v[156:157], v[156:157], off
	ds_read_b128 v[70:73], v221 offset:64
	ds_read_b128 v[166:169], v221 offset:128
	v_add_u32_e32 v0, s14, v205
	s_waitcnt lgkmcnt(2)
	v_mfma_f32_16x16x32_bf16 v[82:85], v[82:85], v[78:81], 0
	v_lshlrev_b64 v[74:75], 13, v[0:1]
	v_lshl_add_u64 v[74:75], v[110:111], 0, v[74:75]
	global_load_dwordx2 v[164:165], v[74:75], off
	global_load_dwordx2 v[162:163], v[74:75], off offset:32
	global_load_dwordx2 v[160:161], v[74:75], off offset:64
	global_load_dwordx2 v[158:159], v[74:75], off offset:96
	ds_read_b128 v[170:173], v221 offset:192
	s_waitcnt lgkmcnt(2)
	v_mfma_f32_16x16x32_bf16 v[70:73], v[70:73], v[86:89], v[82:85]
	v_mov_b32_e32 v53, v54
	v_mul_f32_e32 v54, v54, v61
	s_nop 0
	ds_read_b128 v[82:85], v214 offset:47360
	v_pk_fma_f32 v[52:53], v[52:53], v[60:61], v[54:55] op_sel_hi:[1,1,0]
	s_waitcnt lgkmcnt(2)
	v_mfma_f32_16x16x32_bf16 v[70:73], v[166:169], v[90:93], v[70:73]
	ds_bpermute_b32 v74, v196, v52
	ds_read_b128 v[52:55], v214 offset:47424
	ds_read_b128 v[166:169], v221 offset:4352
	s_waitcnt lgkmcnt(4)
	v_mfma_f32_16x16x32_bf16 v[70:73], v[170:173], v[94:97], v[70:73]
	ds_read_b128 v[170:173], v221 offset:4416
	v_mul_f32_e32 v75, 0xbfb8aa3b, v174
	ds_read_b128 v[174:177], v221 offset:4480
	s_waitcnt lgkmcnt(5)
	v_mfma_f32_16x16x32_bf16 v[82:85], v[82:85], v[62:65], 0
	v_mov_b32_e32 v98, v61
	s_nop 1
	v_pk_mul_f32 v[178:179], v[98:99], v[70:71] op_sel_hi:[0,1]
	v_pk_mul_f32 v[180:181], v[98:99], v[72:73] op_sel_hi:[0,1]
	s_waitcnt lgkmcnt(3)
	v_mfma_f32_16x16x32_bf16 v[82:85], v[52:55], v[66:69], v[82:85]
	ds_read_b128 v[70:73], v221 offset:4544
	v_pk_fma_f32 v[58:59], v[60:61], v[58:59], v[180:181] op_sel_hi:[0,1,1]
	v_pk_fma_f32 v[56:57], v[60:61], v[56:57], v[178:179] op_sel_hi:[0,1,1]
	s_waitcnt lgkmcnt(3)
	v_mfma_f32_16x16x32_bf16 v[52:55], v[166:169], v[78:81], 0
	ds_read_b128 v[178:181], v221 offset:8768
	v_exp_f32_e32 v75, v75
	v_max_f32_e64 v74, |v74|, |v74|
	s_waitcnt lgkmcnt(3)
	v_mfma_f32_16x16x32_bf16 v[166:169], v[170:173], v[86:89], v[52:55]
	ds_read_b128 v[224:227], v221 offset:8832
	v_max_f32_e32 v74, v74, v75
	v_rcp_f32_e32 v74, v74
	s_waitcnt lgkmcnt(3)
	v_mfma_f32_16x16x32_bf16 v[168:171], v[174:177], v[90:93], v[166:169]
	ds_read_b128 v[52:55], v214 offset:49664
	v_pk_mul_f32 v[172:173], v[74:75], v[56:57] op_sel_hi:[0,1]
	s_waitcnt lgkmcnt(3)
	v_mfma_f32_16x16x32_bf16 v[70:73], v[70:73], v[94:97], v[168:171]
	v_mul_f32_e64 v166, v74, v58
	v_mul_f32_e64 v167, v74, v59
	v_mul_f32_e32 v99, v166, v166
	v_mul_f32_e32 v61, v172, v172
	ds_read_b128 v[168:171], v221 offset:8704
	s_waitcnt lgkmcnt(0)
	v_mfma_f32_16x16x32_bf16 v[168:171], v[168:171], v[78:81], 0
	s_nop 0
	v_mul_f32_e64 v228, v98, v70
	v_mul_f32_e64 v229, v98, v71
	v_pk_mul_f32 v[230:231], v[98:99], v[72:73] op_sel_hi:[0,1]
	ds_read_b128 v[70:73], v221 offset:8896
	v_mfma_f32_16x16x32_bf16 v[168:171], v[178:181], v[86:89], v[168:171]
	v_fma_f32 v178, v60, v84, v230
	v_fma_f32 v179, v60, v85, v231
	v_pk_fma_f32 v[180:181], v[60:61], v[82:83], v[228:229] op_sel_hi:[0,1,1]
	ds_read_b128 v[82:85], v215 offset:45056
	ds_read_b128 v[228:231], v215 offset:45120
	v_mfma_f32_16x16x32_bf16 v[224:227], v[224:227], v[90:93], v[168:171]
	ds_read_b128 v[56:59], v214 offset:49728
	v_mul_f32_e32 v75, v173, v173
	v_pk_mul_f32 v[180:181], v[74:75], v[180:181] op_sel_hi:[0,1]
	s_waitcnt lgkmcnt(3)
	v_mfma_f32_16x16x32_bf16 v[70:73], v[70:73], v[94:97], v[224:227]
	v_mul_f32_e64 v170, v74, v178
	v_mul_f32_e64 v171, v74, v179
	v_mul_f32_e32 v233, v167, v167
	v_mov_b32_e32 v232, v171
	ds_read_b128 v[224:227], v216
	v_mfma_f32_16x16x32_bf16 v[174:177], v[52:55], v[62:65], 0
	s_nop 1
	v_mul_f32_e64 v168, v98, v70
	v_mul_f32_e64 v169, v98, v71
	v_pk_mul_f32 v[178:179], v[98:99], v[72:73] op_sel_hi:[0,1]
	v_add_f32_e32 v182, v172, v173
	s_waitcnt lgkmcnt(3)
	v_mfma_f32_16x16x32_bf16 v[62:65], v[82:85], v[62:65], 0
	v_mul_f32_e32 v82, v170, v170
	v_pk_fma_f32 v[220:221], v[170:171], v[170:171], v[82:83] op_sel_hi:[1,1,0]
	ds_read_b128 v[82:85], v216 offset:64
	s_waitcnt lgkmcnt(2)
	v_mfma_f32_16x16x32_bf16 v[174:177], v[56:59], v[66:69], v[174:177]
	v_add_f32_e32 v188, v166, v167
	v_mul_f32_e32 v183, v180, v180
	v_mul_f32_e32 v189, v181, v181
	v_mfma_f32_16x16x32_bf16 v[62:65], v[228:231], v[66:69], v[62:65]
	ds_read_b128 v[66:69], v216 offset:128
	s_nop 2
	v_pk_fma_f32 v[176:177], v[60:61], v[176:177], v[178:179] op_sel_hi:[0,1,1]
	v_pk_fma_f32 v[168:169], v[60:61], v[174:175], v[168:169] op_sel_hi:[0,1,1]
	s_waitcnt lgkmcnt(2)
	v_mfma_f32_16x16x32_bf16 v[70:73], v[224:227], v[78:81], 0
	ds_read_b128 v[78:81], v216 offset:192
	v_pk_mul_f32 v[174:175], v[74:75], v[176:177] op_sel_hi:[0,1]
	v_pk_mul_f32 v[178:179], v[74:75], v[168:169] op_sel_hi:[0,1]
	s_waitcnt lgkmcnt(2)
	v_mfma_f32_16x16x32_bf16 v[70:73], v[82:85], v[86:89], v[70:73]
	v_mul_f32_e32 v83, v178, v178
	v_mul_f32_e32 v85, v175, v175
	v_mov_b32_e32 v220, v1
	s_waitcnt lgkmcnt(1)
	v_mfma_f32_16x16x32_bf16 v[66:69], v[66:69], v[90:93], v[70:73]
	v_mov_b32_e32 v82, v178
	v_mov_b32_e32 v84, v175
	s_waitcnt lgkmcnt(0)
	v_mfma_f32_16x16x32_bf16 v[66:69], v[78:81], v[94:97], v[66:69]
	v_mul_f32_e32 v71, v179, v179
	v_mul_f32_e32 v73, v174, v174
	v_mov_b32_e32 v70, v179
	v_mov_b32_e32 v72, v174
	v_pk_add_f32 v[70:71], v[82:83], v[70:71]
	s_nop 2
	v_pk_mul_f32 v[66:67], v[98:99], v[66:67] op_sel_hi:[0,1]
	v_pk_mul_f32 v[68:69], v[98:99], v[68:69] op_sel_hi:[0,1]
	v_pk_fma_f32 v[64:65], v[60:61], v[64:65], v[68:69] op_sel_hi:[0,1,1]
	v_pk_fma_f32 v[62:63], v[60:61], v[62:63], v[66:67] op_sel_hi:[0,1,1]
	v_pk_mul_f32 v[168:169], v[74:75], v[64:65] op_sel_hi:[0,1]
	v_pk_mul_f32 v[176:177], v[74:75], v[62:63] op_sel_hi:[0,1]
	v_mov_b32_e32 v60, v180
	v_mov_b32_e32 v74, v181
	v_mov_b32_e32 v98, v170
	v_pk_add_f32 v[60:61], v[60:61], v[74:75]
	v_pk_add_f32 v[74:75], v[98:99], v[232:233]
	v_mul_f32_e32 v63, v176, v176
	v_pk_add_f32 v[60:61], v[60:61], v[74:75]
	v_pk_add_f32 v[74:75], v[182:183], v[188:189]
	v_mul_f32_e32 v65, v177, v177
	v_mul_f32_e32 v67, v168, v168
	v_mul_f32_e32 v69, v169, v169
	v_pk_add_f32 v[74:75], v[74:75], v[220:221]
	v_pk_add_f32 v[72:73], v[72:73], v[84:85]
	v_mov_b32_e32 v62, v176
	v_mov_b32_e32 v64, v177
	v_mov_b32_e32 v66, v168
	v_mov_b32_e32 v68, v169
	v_pk_add_f32 v[60:61], v[60:61], v[74:75]
	v_pk_add_f32 v[70:71], v[70:71], v[72:73]
	v_pk_add_f32 v[62:63], v[62:63], v[64:65]
	v_pk_add_f32 v[64:65], v[66:67], v[68:69]
	v_pk_add_f32 v[60:61], v[60:61], v[70:71]
	v_pk_add_f32 v[62:63], v[62:63], v[64:65]
	s_nop 0
	v_pk_add_f32 v[60:61], v[60:61], v[62:63]
	ds_bpermute_b32 v62, v198, v60
	ds_bpermute_b32 v63, v198, v61
	s_waitcnt lgkmcnt(0)
	v_pk_add_f32 v[60:61], v[60:61], v[62:63]
	ds_bpermute_b32 v62, v199, v60
	ds_bpermute_b32 v63, v199, v61
	s_and_saveexec_b64 s[14:15], s[2:3]
	s_cbranch_execz .LBB0_360
	s_waitcnt lgkmcnt(0)
	v_pk_add_f32 v[52:53], v[60:61], v[62:63]
	ds_write_b64 v223, v[52:53]
	ds_read_b128 v[52:55], v214 offset:49664
	ds_read_b128 v[56:59], v214 offset:49728

.LBB0_388:
	s_add_i32 s8, s22, 2
	s_and_b64 s[6:7], s[6:7], exec
	s_cselect_b32 s0, s8, 64
	s_add_i32 s0, s0, -1
	s_lshl_b64 s[6:7], s[0:1], 6
	s_add_u32 s6, s6, s16
	s_addc_u32 s7, s7, 0
	s_add_i32 s0, s0, s17
	v_mov_b32_e32 v1, s7
	v_or_b32_e32 v0, s6, v78
	s_lshl_b64 s[10:11], s[0:1], 14
	v_lshlrev_b64 v[0:1], 10, v[0:1]
	s_add_u32 s10, s14, s10
	v_lshl_add_u64 v[0:1], v[76:77], 0, v[0:1]
	s_addc_u32 s11, s15, s11
	v_lshlrev_b32_e32 v190, 1, v74
	global_load_dwordx4 v[0:3], v[0:1], off
	s_nop 0
	global_load_dwordx4 v[16:19], v190, s[10:11]
	ds_read_b128 v[40:43], v181 offset:45056
	v_lshl_add_u64 v[24:25], s[6:7], 0, v[80:81]
	v_lshlrev_b64 v[24:25], 10, v[24:25]
	v_lshl_add_u64 v[24:25], v[76:77], 0, v[24:25]
	v_add_u32_e32 v198, v161, v162
	v_add_u32_e32 v197, v163, v168
	ds_read_b128 v[138:141], v198 offset:17408
	ds_read_b128 v[48:51], v181 offset:45120
	global_load_dwordx4 v[24:27], v[24:25], off
	s_nop 0
	global_load_dwordx4 v[44:47], v173, s[10:11]
	ds_read_b128 v[156:159], v198 offset:17472
	ds_read_b128 v[52:55], v197 offset:63488
	s_waitcnt lgkmcnt(3)
	v_mfma_f32_16x16x32_bf16 v[40:43], v[40:43], v[138:141], 0
	ds_read_b128 v[200:203], v180
	ds_read_b128 v[64:67], v197 offset:63552
	s_lshl_b64 s[6:7], s[0:1], 13
	v_lshl_add_u64 v[124:125], v[86:87], 0, s[6:7]
	s_waitcnt lgkmcnt(3)
	v_mfma_f32_16x16x32_bf16 v[146:149], v[48:51], v[156:159], v[40:43]
	ds_read_b128 v[204:207], v180 offset:64
	s_nop 1
	ds_read_b128 v[40:43], v197 offset:63616
	s_lshl_b64 s[6:7], s[0:1], 9
	v_lshl_add_u64 v[128:129], v[90:91], 0, s[6:7]
	s_waitcnt lgkmcnt(3)
	v_mfma_f32_16x16x32_bf16 v[48:51], v[52:55], v[200:203], 0
	ds_read_b128 v[208:211], v180 offset:128
	ds_read_b128 v[52:55], v197 offset:63680
	v_add_u32_e32 v195, v163, v169
	s_lshl_b32 s0, s22, 6
	s_waitcnt lgkmcnt(3)
	v_mfma_f32_16x16x32_bf16 v[48:51], v[64:67], v[204:207], v[48:51]
	ds_read_b128 v[212:215], v180 offset:192
	ds_read_b128 v[64:67], v181 offset:47360
	s_or_b32 s9, s0, 64
	v_add_lshl_u32 v72, s9, v79, 13
	s_waitcnt lgkmcnt(3)
	v_mfma_f32_16x16x32_bf16 v[68:71], v[40:43], v[208:211], v[48:51]
	global_load_dwordx4 v[40:43], v[124:125], off
	s_nop 1
	global_load_dwordx4 v[48:51], v[128:129], off
	ds_read_b128 v[124:127], v181 offset:47424
	v_lshl_add_u64 v[134:135], v[82:83], 0, v[72:73]
	s_waitcnt lgkmcnt(2)
	v_mfma_f32_16x16x32_bf16 v[150:153], v[52:55], v[212:215], v[68:71]
	v_add_co_u32_e32 v136, vcc, s18, v134
	v_add_u32_e32 v72, s0, v172
	s_nop 0
	ds_read_b128 v[68:71], v195 offset:63488
	s_waitcnt lgkmcnt(2)
	v_mfma_f32_16x16x32_bf16 v[52:55], v[64:67], v[138:141], 0
	ds_read_b128 v[64:67], v195 offset:63552
	v_addc_co_u32_e32 v137, vcc, 0, v135, vcc
	s_waitcnt lgkmcnt(2)
	v_mfma_f32_16x16x32_bf16 v[216:219], v[124:127], v[156:159], v[52:55]
	s_nop 3
	global_load_dwordx4 v[52:55], v[128:129], off offset:64
	global_load_dwordx2 v[124:125], v[134:135], off
	ds_read_b128 v[126:129], v195 offset:63616
	ds_read_b128 v[130:133], v195 offset:63680
	s_waitcnt lgkmcnt(3)
	v_mfma_f32_16x16x32_bf16 v[68:71], v[68:71], v[200:203], 0
	v_add_co_u32_e32 v142, vcc, s19, v134
	v_add_u32_e32 v196, v163, v170
	s_waitcnt lgkmcnt(2)
	v_mfma_f32_16x16x32_bf16 v[64:67], v[64:67], v[204:207], v[68:71]
	v_addc_co_u32_e32 v143, vcc, 0, v135, vcc
	ds_read_b128 v[224:227], v196 offset:63488
	s_waitcnt lgkmcnt(2)
	v_mfma_f32_16x16x32_bf16 v[64:67], v[126:129], v[208:211], v[64:67]
	ds_read_b128 v[68:71], v181 offset:49664
	v_add_co_u32_e32 v126, vcc, s20, v134
	s_waitcnt lgkmcnt(2)
	v_mfma_f32_16x16x32_bf16 v[220:223], v[130:133], v[212:215], v[64:67]
	v_addc_co_u32_e32 v127, vcc, 0, v135, vcc
	v_lshlrev_b64 v[128:129], 13, v[72:73]
	s_nop 1
	ds_read_b128 v[64:67], v181 offset:49728
	s_waitcnt lgkmcnt(1)
	v_mfma_f32_16x16x32_bf16 v[132:135], v[68:71], v[138:141], 0
	v_lshl_add_u64 v[154:155], v[84:85], 0, v[128:129]
	global_load_dwordx2 v[130:131], v[136:137], off
	global_load_dwordx2 v[128:129], v[142:143], off
	s_nop 0
	global_load_dwordx2 v[126:127], v[126:127], off
	s_nop 0
	global_load_dwordx2 v[144:145], v[154:155], off
	ds_read_b128 v[232:235], v196 offset:63552
	s_waitcnt lgkmcnt(1)
	v_mfma_f32_16x16x32_bf16 v[228:231], v[64:67], v[156:159], v[132:135]
	global_load_dwordx2 v[136:137], v[154:155], off offset:32
	s_nop 1
	global_load_dwordx2 v[134:135], v[154:155], off offset:64
	global_load_dwordx2 v[132:133], v[154:155], off offset:96
	ds_read_b128 v[236:239], v196 offset:63616
	ds_read_b128 v[240:243], v196 offset:63680
	v_mfma_f32_16x16x32_bf16 v[224:227], v[224:227], v[200:203], 0
	v_add_f32_e64 v148, v148, v152
	v_add_f32_e64 v149, v149, v153
	v_pk_add_f32 v[152:153], v[146:147], v[150:151]
	v_pk_add_f32 v[146:147], v[218:219], v[222:223]
	s_waitcnt lgkmcnt(2)
	v_mfma_f32_16x16x32_bf16 v[224:227], v[232:235], v[204:207], v[224:227]
	ds_read_b128 v[232:235], v182 offset:45056
	v_pk_add_f32 v[154:155], v[216:217], v[220:221]
	ds_read_b128 v[216:219], v183 offset:63552
	s_waitcnt lgkmcnt(3)
	v_mfma_f32_16x16x32_bf16 v[224:227], v[236:239], v[208:211], v[224:227]
	ds_read_b128 v[236:239], v182 offset:45120
	ds_read_b128 v[220:223], v183 offset:63680
	v_mul_f32_e32 v142, v146, v146
	s_waitcnt lgkmcnt(4)
	v_mfma_f32_16x16x32_bf16 v[224:227], v[240:243], v[212:215], v[224:227]
	ds_read_b128 v[240:243], v183 offset:63488
	v_add_f32_e32 v192, v152, v153
	v_add_f32_e32 v244, v148, v149
	s_waitcnt lgkmcnt(4)
	v_mfma_f32_16x16x32_bf16 v[138:141], v[232:235], v[138:141], 0
	v_mul_f32_e32 v247, v152, v152
	v_mul_f32_e32 v249, v153, v153
	v_mul_f32_e32 v251, v148, v148
	s_waitcnt lgkmcnt(2)
	v_mfma_f32_16x16x32_bf16 v[156:159], v[236:239], v[156:159], v[138:141]
	v_mul_f32_e32 v253, v149, v149
	v_mul_f32_e32 v193, v154, v154
	v_mul_f32_e32 v245, v155, v155
	ds_read_b128 v[138:141], v183 offset:63616
	s_waitcnt lgkmcnt(1)
	v_mfma_f32_16x16x32_bf16 v[200:203], v[240:243], v[200:203], 0
	v_fma_f32 v232, v146, v146, v142
	v_fma_f32 v233, v147, v147, v142
	v_pk_add_f32 v[142:143], v[230:231], v[226:227]
	v_pk_add_f32 v[150:151], v[228:229], v[224:225]
	v_mfma_f32_16x16x32_bf16 v[200:203], v[216:219], v[204:207], v[200:203]
	v_mov_b32_e32 v246, v154
	v_mov_b32_e32 v248, v155
	v_mov_b32_e32 v250, v146
	s_waitcnt lgkmcnt(0)
	v_mfma_f32_16x16x32_bf16 v[138:141], v[138:141], v[208:211], v[200:203]
	v_mov_b32_e32 v252, v147
	v_mul_f32_e32 v205, v150, v150
	v_mul_f32_e32 v207, v151, v151
	v_mfma_f32_16x16x32_bf16 v[200:203], v[220:223], v[212:215], v[138:141]
	v_mul_f32_e32 v209, v142, v142
	v_mul_f32_e32 v211, v143, v143
	v_pk_add_f32 v[212:213], v[246:247], v[248:249]
	v_pk_add_f32 v[214:215], v[250:251], v[252:253]
	v_pk_add_f32 v[192:193], v[192:193], v[244:245]
	s_nop 2
	v_pk_add_f32 v[138:139], v[158:159], v[202:203]
	v_and_b32_e32 v158, 64, v174
	v_pk_add_f32 v[140:141], v[156:157], v[200:201]
	v_xor_b32_e32 v156, 16, v174
	v_add_u32_e32 v194, 64, v158
	v_cmp_lt_i32_e32 vcc, v156, v194
	v_mov_b32_e32 v232, v73
	v_mov_b32_e32 v204, v150
	v_cndmask_b32_e32 v156, v174, v156, vcc
	v_mov_b32_e32 v206, v151
	v_mov_b32_e32 v208, v142
	v_mov_b32_e32 v210, v143
	v_mul_f32_e32 v157, v140, v140
	v_mul_f32_e32 v159, v141, v141
	v_mul_f32_e32 v201, v138, v138
	v_mul_f32_e32 v203, v139, v139
	v_lshlrev_b32_e32 v191, 2, v156
	v_pk_add_f32 v[212:213], v[212:213], v[214:215]
	v_pk_add_f32 v[192:193], v[192:193], v[232:233]
	v_pk_add_f32 v[204:205], v[204:205], v[206:207]
	v_pk_add_f32 v[206:207], v[208:209], v[210:211]
	v_mov_b32_e32 v156, v140
	v_mov_b32_e32 v158, v141
	v_mov_b32_e32 v200, v138
	v_mov_b32_e32 v202, v139
	v_pk_add_f32 v[192:193], v[212:213], v[192:193]
	v_pk_add_f32 v[204:205], v[204:205], v[206:207]
	v_pk_add_f32 v[156:157], v[156:157], v[158:159]
	v_pk_add_f32 v[158:159], v[200:201], v[202:203]
	v_pk_add_f32 v[192:193], v[192:193], v[204:205]
	v_pk_add_f32 v[156:157], v[156:157], v[158:159]
	s_nop 0
	v_pk_add_f32 v[156:157], v[192:193], v[156:157]
	ds_bpermute_b32 v158, v191, v156
	ds_bpermute_b32 v159, v191, v157
	v_xor_b32_e32 v192, 32, v174
	v_cmp_lt_i32_e32 vcc, v192, v194
	s_waitcnt lgkmcnt(0)
	v_pk_add_f32 v[156:157], v[156:157], v[158:159]
	v_cndmask_b32_e32 v192, v174, v192, vcc
	v_lshlrev_b32_e32 v199, 2, v192
	ds_bpermute_b32 v158, v199, v156
	ds_bpermute_b32 v159, v199, v157
	s_and_saveexec_b64 s[6:7], s[2:3]
	s_cbranch_execz .LBB0_390
	s_waitcnt lgkmcnt(0)
	v_pk_add_f32 v[156:157], v[156:157], v[158:159]
	ds_write_b64 v164, v[156:157]
.LBB0_390:
	s_or_b64 exec, exec, s[6:7]
	s_waitcnt lgkmcnt(0)
	ds_read_b128 v[156:159], v187 offset:26624
	ds_read_b128 v[200:203], v181 offset:45056
	ds_read_b128 v[204:207], v187 offset:26688
	ds_read_b128 v[208:211], v181 offset:45120
	ds_read_b128 v[216:219], v187 offset:28928
	ds_read_b128 v[220:223], v187 offset:28992
	v_add_u32_e32 v194, v165, v168
	s_waitcnt lgkmcnt(4)
	v_mfma_f32_16x16x32_bf16 v[212:215], v[156:159], v[200:203], 0
	v_add_u32_e32 v193, v165, v169
	v_add_u32_e32 v192, v165, v170
	s_min_u32 s0, s22, 61
	s_waitcnt lgkmcnt(1)
	v_mfma_f32_16x16x32_bf16 v[200:203], v[216:219], v[200:203], 0
	s_add_i32 s6, s0, 2
	s_lshl_b32 s0, s6, 6
	s_add_i32 s0, s0, s16
	v_mfma_f32_16x16x32_bf16 v[212:215], v[204:207], v[208:211], v[212:215]
	s_add_i32 s10, s6, s17
	s_lshl_b32 s6, s10, 14
	s_add_u32 s6, s14, s6
	s_waitcnt lgkmcnt(0)
	v_mfma_f32_16x16x32_bf16 v[200:203], v[220:223], v[208:211], v[200:203]
	ds_read_b128 v[208:211], v181 offset:47360
	ds_read_b128 v[224:227], v181 offset:47424
	s_nop 0
	v_pk_fma_f32 v[98:99], v[62:63], v[98:99], v[214:215]
	v_pk_fma_f32 v[92:93], v[60:61], v[92:93], v[212:213]
	s_waitcnt lgkmcnt(1)
	v_mfma_f32_16x16x32_bf16 v[228:231], v[156:159], v[208:211], 0
	ds_read_b128 v[212:215], v181 offset:51968
	v_pk_fma_f32 v[112:113], v[58:59], v[112:113], v[202:203]
	v_pk_fma_f32 v[108:109], v[56:57], v[108:109], v[200:201]
	v_mfma_f32_16x16x32_bf16 v[208:211], v[216:219], v[208:211], 0
	s_addc_u32 s7, s15, 0
	s_waitcnt lgkmcnt(1)
	v_mfma_f32_16x16x32_bf16 v[228:231], v[204:207], v[224:227], v[228:231]
	v_mfma_f32_16x16x32_bf16 v[208:211], v[220:223], v[224:227], v[208:211]
	v_mfma_f32_16x16x32_bf16 v[224:227], v[156:159], v[68:71], 0
	s_nop 5
	v_fma_f32 v96, v62, v96, v230
	v_fma_f32 v97, v63, v97, v231
	v_pk_fma_f32 v[94:95], v[60:61], v[94:95], v[228:229]
	v_pk_fma_f32 v[110:111], v[56:57], v[110:111], v[208:209]
	v_mfma_f32_16x16x32_bf16 v[68:71], v[216:219], v[68:71], 0
	v_fma_f32 v116, v58, v116, v210
	v_fma_f32 v117, v59, v117, v211
	v_mfma_f32_16x16x32_bf16 v[224:227], v[204:207], v[64:67], v[224:227]
	v_mfma_f32_16x16x32_bf16 v[64:67], v[220:223], v[64:67], v[68:71]
	s_nop 3
	ds_read_b128 v[68:71], v181 offset:52032
	s_waitcnt lgkmcnt(1)
	v_mfma_f32_16x16x32_bf16 v[156:159], v[156:159], v[212:215], 0
	v_fma_f32 v104, v62, v104, v226
	v_fma_f32 v105, v63, v105, v227
	v_pk_fma_f32 v[100:101], v[60:61], v[100:101], v[224:225]
	v_pk_fma_f32 v[114:115], v[56:57], v[114:115], v[64:65]
	s_waitcnt lgkmcnt(0)
	v_mfma_f32_16x16x32_bf16 v[156:159], v[204:207], v[68:71], v[156:159]
	s_barrier
	v_mfma_f32_16x16x32_bf16 v[200:203], v[216:219], v[212:215], 0
	v_fma_f32 v120, v58, v120, v66
	v_fma_f32 v121, v59, v121, v67
	s_nop 3
	v_pk_fma_f32 v[106:107], v[62:63], v[106:107], v[158:159]
	v_pk_fma_f32 v[102:103], v[60:61], v[102:103], v[156:157]
	v_mfma_f32_16x16x32_bf16 v[60:63], v[220:223], v[68:71], v[200:203]
	s_nop 7
	v_pk_fma_f32 v[118:119], v[56:57], v[118:119], v[60:61]
	v_cvt_pk_bf16_f32 v56, v92, v93
	v_cvt_pk_bf16_f32 v57, v98, v99
	ds_write_b64 v194, v[56:57] offset:63488
	v_cvt_pk_bf16_f32 v56, v94, v95
	v_cvt_pk_bf16_f32 v57, v96, v97
	ds_write_b64 v193, v[56:57] offset:63488
	v_cvt_pk_bf16_f32 v56, v100, v101
	v_cvt_pk_bf16_f32 v57, v104, v105
	ds_write_b64 v192, v[56:57] offset:63488
	v_cvt_pk_bf16_f32 v56, v102, v103
	v_cvt_pk_bf16_f32 v57, v106, v107
	ds_write_b64 v188, v[56:57] offset:63488
	v_cvt_pk_bf16_f32 v56, v108, v109
	v_cvt_pk_bf16_f32 v57, v112, v113
	ds_write_b64 v194, v[56:57] offset:63520
	v_cvt_pk_bf16_f32 v56, v110, v111
	v_cvt_pk_bf16_f32 v57, v116, v117
	v_pk_fma_f32 v[122:123], v[58:59], v[122:123], v[62:63]
	ds_write_b64 v193, v[56:57] offset:63520
	v_cvt_pk_bf16_f32 v56, v114, v115
	v_cvt_pk_bf16_f32 v57, v120, v121
	ds_write_b64 v192, v[56:57] offset:63520
	v_cvt_pk_bf16_f32 v56, v118, v119
	v_cvt_pk_bf16_f32 v57, v122, v123
	ds_write_b64 v188, v[56:57] offset:63520
	ds_read_b128 v[56:59], v166
	ds_read_b128 v[60:63], v167
	s_waitcnt vmcnt(3) lgkmcnt(1)
	v_lshlrev_b32_e32 v58, 16, v145
	v_add_f32_e32 v56, v57, v59
	v_mul_f32_e32 v56, 0x3c000000, v56
	v_max_f32_e32 v56, 0, v56
	v_add_f32_e32 v56, 0x3727c5ac, v56
	v_rsq_f32_e32 v64, v56
	v_lshlrev_b64 v[56:57], 11, v[72:73]
	v_lshl_add_u64 v[66:67], v[88:89], 0, v[56:57]
	v_lshlrev_b32_e32 v56, 16, v144
	v_and_b32_e32 v57, 0xffff0000, v144
	v_and_b32_e32 v59, 0xffff0000, v145
	v_pk_mul_f32 v[56:57], v[152:153], v[56:57]
	v_pk_mul_f32 v[58:59], v[148:149], v[58:59]
	v_pk_mul_f32 v[56:57], v[56:57], v[64:65] op_sel_hi:[1,0]
	v_pk_mul_f32 v[58:59], v[58:59], v[64:65] op_sel_hi:[1,0]
	s_waitcnt lgkmcnt(0)
	v_pk_mul_f32 v[56:57], v[60:61], v[56:57]
	v_pk_mul_f32 v[58:59], v[62:63], v[58:59]
	v_cvt_pk_bf16_f32 v56, v56, v57
	v_cvt_pk_bf16_f32 v57, v58, v59
	global_store_dwordx2 v[66:67], v[56:57], off
	ds_read_b128 v[56:59], v167 offset:64
	s_waitcnt vmcnt(3)
	v_lshlrev_b32_e32 v60, 16, v136
	v_and_b32_e32 v61, 0xffff0000, v136
	v_pk_mul_f32 v[60:61], v[154:155], v[60:61]
	s_nop 0
	v_pk_mul_f32 v[68:69], v[60:61], v[64:65] op_sel_hi:[1,0]
	ds_read_b128 v[60:63], v167 offset:128
	s_waitcnt lgkmcnt(1)
	v_pk_mul_f32 v[56:57], v[56:57], v[68:69]
	v_lshlrev_b32_e32 v68, 16, v137
	v_and_b32_e32 v69, 0xffff0000, v137
	v_pk_mul_f32 v[68:69], v[146:147], v[68:69]
	v_cvt_pk_bf16_f32 v56, v56, v57
	v_pk_mul_f32 v[68:69], v[68:69], v[64:65] op_sel_hi:[1,0]
	s_nop 0
	v_pk_mul_f32 v[58:59], v[58:59], v[68:69]
	s_nop 0
	v_cvt_pk_bf16_f32 v57, v58, v59
	global_store_dwordx2 v[66:67], v[56:57], off offset:32
	s_waitcnt vmcnt(3)
	v_lshlrev_b32_e32 v56, 16, v134
	v_and_b32_e32 v57, 0xffff0000, v134
	v_lshlrev_b32_e32 v58, 16, v135
	v_and_b32_e32 v59, 0xffff0000, v135
	v_pk_mul_f32 v[56:57], v[150:151], v[56:57]
	v_pk_mul_f32 v[58:59], v[142:143], v[58:59]
	v_pk_mul_f32 v[56:57], v[56:57], v[64:65] op_sel_hi:[1,0]
	v_pk_mul_f32 v[58:59], v[58:59], v[64:65] op_sel_hi:[1,0]
	s_waitcnt lgkmcnt(0)
	v_pk_mul_f32 v[56:57], v[60:61], v[56:57]
	v_pk_mul_f32 v[58:59], v[62:63], v[58:59]
	v_cvt_pk_bf16_f32 v56, v56, v57
	v_cvt_pk_bf16_f32 v57, v58, v59
	global_store_dwordx2 v[66:67], v[56:57], off offset:64
	ds_read_b128 v[56:59], v167 offset:192
	s_waitcnt vmcnt(3)
	v_lshlrev_b32_e32 v60, 16, v132
	v_and_b32_e32 v61, 0xffff0000, v132
	v_pk_mul_f32 v[60:61], v[140:141], v[60:61]
	s_nop 0
	v_pk_mul_f32 v[60:61], v[60:61], v[64:65] op_sel_hi:[1,0]
	s_waitcnt lgkmcnt(0)
	v_pk_mul_f32 v[56:57], v[60:61], v[56:57]
	v_lshlrev_b32_e32 v60, 16, v133
	v_and_b32_e32 v61, 0xffff0000, v133
	v_pk_mul_f32 v[60:61], v[138:139], v[60:61]
	v_cvt_pk_bf16_f32 v56, v56, v57
	v_pk_mul_f32 v[60:61], v[60:61], v[64:65] op_sel_hi:[1,0]
	s_nop 0
	v_pk_mul_f32 v[58:59], v[60:61], v[58:59]
	s_nop 0
	v_cvt_pk_bf16_f32 v57, v58, v59
	global_store_dwordx2 v[66:67], v[56:57], off offset:96
	ds_write_b128 v175, v[0:3]
	ds_write_b128 v176, v[16:19] offset:26624
	ds_write_b128 v177, v[24:27]
	ds_write_b128 v178, v[44:47] offset:26624
	ds_write_b128 v160, v[40:43] offset:17408
	v_lshlrev_b32_e32 v0, 16, v124
	v_and_b32_e32 v2, 0xffff0000, v124
	v_lshlrev_b32_e32 v1, 16, v130
	v_and_b32_e32 v3, 0xffff0000, v130
	v_lshlrev_b32_e32 v44, 16, v128
	v_and_b32_e32 v45, 0xffff0000, v128
	v_lshlrev_b32_e32 v16, 16, v126
	v_and_b32_e32 v17, 0xffff0000, v126
	v_lshlrev_b32_e32 v24, 16, v125
	v_and_b32_e32 v25, 0xffff0000, v125
	v_lshlrev_b32_e32 v26, 16, v131
	v_and_b32_e32 v27, 0xffff0000, v131
	v_lshlrev_b32_e32 v46, 16, v129
	v_and_b32_e32 v47, 0xffff0000, v129
	v_lshlrev_b32_e32 v18, 16, v127
	v_and_b32_e32 v19, 0xffff0000, v127
	v_cvt_pk_bf16_f32 v0, v0, v1
	v_cvt_pk_bf16_f32 v1, v44, v16
	v_cvt_pk_bf16_f32 v2, v2, v3
	v_cvt_pk_bf16_f32 v3, v45, v17
	ds_write2_b64 v189, v[0:1], v[2:3] offset1:18
	v_cvt_pk_bf16_f32 v0, v24, v26
	v_cvt_pk_bf16_f32 v1, v46, v18
	v_cvt_pk_bf16_f32 v2, v25, v27
	v_cvt_pk_bf16_f32 v3, v47, v19
	ds_write2_b64 v189, v[0:1], v[2:3] offset0:36 offset1:54
	s_waitcnt lgkmcnt(0)
	s_barrier
	ds_read_b128 v[0:3], v181 offset:45056
	v_or_b32_e32 v24, s0, v78
	v_mov_b32_e32 v25, v75
	v_lshlrev_b64 v[44:45], 10, v[24:25]
	ds_read_b128 v[138:141], v198 offset:17408
	ds_read_b128 v[24:27], v181 offset:45120
	v_lshl_add_u64 v[16:17], v[76:77], 0, v[44:45]
	ds_read_b128 v[44:47], v197 offset:63488
	ds_read_b128 v[200:203], v180
	ds_read_b128 v[156:159], v198 offset:17472
	ds_read_b128 v[40:43], v197 offset:63552
	s_waitcnt lgkmcnt(5)
	v_mfma_f32_16x16x32_bf16 v[0:3], v[0:3], v[138:141], 0
	v_lshl_add_u64 v[18:19], s[0:1], 0, v[80:81]
	v_lshlrev_b64 v[18:19], 10, v[18:19]
	v_lshl_add_u64 v[18:19], v[76:77], 0, v[18:19]
	s_waitcnt lgkmcnt(1)
	v_mfma_f32_16x16x32_bf16 v[146:149], v[24:27], v[156:159], v[0:3]
	s_nop 2
	global_load_dwordx4 v[0:3], v[16:17], off
	global_load_dwordx4 v[24:27], v[18:19], off
	ds_read_b128 v[204:207], v180 offset:64
	ds_read_b128 v[60:63], v197 offset:63616
	v_mfma_f32_16x16x32_bf16 v[56:59], v[44:47], v[200:203], 0
	global_load_dwordx4 v[16:19], v190, s[6:7]
	global_load_dwordx4 v[44:47], v173, s[6:7]
	ds_read_b128 v[208:211], v180 offset:128
	ds_read_b128 v[64:67], v197 offset:63680
	ds_read_b128 v[212:215], v180 offset:192
	s_waitcnt lgkmcnt(4)
	v_mfma_f32_16x16x32_bf16 v[40:43], v[40:43], v[204:207], v[56:59]
	s_lshl_b32 s0, s10, 13
	s_waitcnt lgkmcnt(2)
	v_mfma_f32_16x16x32_bf16 v[40:43], v[60:63], v[208:211], v[40:43]
	ds_read_b128 v[60:63], v181 offset:47360
	v_lshl_add_u64 v[56:57], v[86:87], 0, s[0:1]
	s_lshl_b32 s0, s10, 9
	s_waitcnt lgkmcnt(1)
	v_mfma_f32_16x16x32_bf16 v[150:153], v[64:67], v[212:215], v[40:43]
	ds_read_b128 v[64:67], v181 offset:47424
	v_lshl_add_u64 v[124:125], v[90:91], 0, s[0:1]
	s_nop 0
	global_load_dwordx4 v[40:43], v[56:57], off
	s_nop 0
	global_load_dwordx4 v[56:59], v[124:125], off offset:64
	ds_read_b128 v[68:71], v195 offset:63488
	s_waitcnt lgkmcnt(2)
	v_mfma_f32_16x16x32_bf16 v[60:63], v[60:63], v[138:141], 0
	s_min_u32 s0, s22, 61
	s_lshl_b32 s0, s0, 18
	v_add_lshl_u32 v72, v171, s0, 1
	s_waitcnt lgkmcnt(1)
	v_mfma_f32_16x16x32_bf16 v[216:219], v[64:67], v[156:159], v[60:63]
	ds_read_b128 v[64:67], v195 offset:63552
	v_lshl_add_u64 v[134:135], v[82:83], 0, v[72:73]
	s_nop 0
	global_load_dwordx4 v[60:63], v[124:125], off
	s_nop 0
	global_load_dwordx2 v[124:125], v[134:135], off
	ds_read_b128 v[126:129], v195 offset:63616
	ds_read_b128 v[130:133], v195 offset:63680
	s_waitcnt lgkmcnt(3)
	v_mfma_f32_16x16x32_bf16 v[68:71], v[68:71], v[200:203], 0
	v_add_co_u32_e32 v136, vcc, s18, v134
	v_add_u32_e32 v72, s9, v172
	s_waitcnt lgkmcnt(2)
	v_mfma_f32_16x16x32_bf16 v[64:67], v[64:67], v[204:207], v[68:71]
	v_addc_co_u32_e32 v137, vcc, 0, v135, vcc
	v_add_co_u32_e32 v142, vcc, s19, v134
	s_waitcnt lgkmcnt(1)
	v_mfma_f32_16x16x32_bf16 v[64:67], v[126:129], v[208:211], v[64:67]
	ds_read_b128 v[68:71], v181 offset:49664
	v_addc_co_u32_e32 v143, vcc, 0, v135, vcc
	s_waitcnt lgkmcnt(1)
	v_mfma_f32_16x16x32_bf16 v[220:223], v[130:133], v[212:215], v[64:67]
	v_add_co_u32_e32 v128, vcc, s20, v134
	v_lshlrev_b64 v[126:127], 13, v[72:73]
	s_nop 1
	ds_read_b128 v[64:67], v181 offset:49728
	v_addc_co_u32_e32 v129, vcc, 0, v135, vcc
	s_waitcnt lgkmcnt(1)
	v_mfma_f32_16x16x32_bf16 v[132:135], v[68:71], v[138:141], 0
	v_lshl_add_u64 v[154:155], v[84:85], 0, v[126:127]
	ds_read_b128 v[224:227], v196 offset:63488
	global_load_dwordx2 v[130:131], v[136:137], off
	global_load_dwordx2 v[126:127], v[142:143], off
	s_nop 0
	global_load_dwordx2 v[128:129], v[128:129], off
	s_nop 0
	global_load_dwordx2 v[144:145], v[154:155], off
	s_waitcnt lgkmcnt(1)
	v_mfma_f32_16x16x32_bf16 v[228:231], v[64:67], v[156:159], v[132:135]
	ds_read_b128 v[232:235], v196 offset:63552
	global_load_dwordx2 v[136:137], v[154:155], off offset:32
	s_nop 0
	global_load_dwordx2 v[134:135], v[154:155], off offset:64
	global_load_dwordx2 v[132:133], v[154:155], off offset:96
	ds_read_b128 v[236:239], v196 offset:63616
	ds_read_b128 v[240:243], v196 offset:63680
	s_waitcnt lgkmcnt(3)
	v_mfma_f32_16x16x32_bf16 v[224:227], v[224:227], v[200:203], 0
	v_add_f32_e64 v148, v148, v152
	v_add_f32_e64 v149, v149, v153
	v_pk_add_f32 v[152:153], v[146:147], v[150:151]
	v_pk_add_f32 v[146:147], v[218:219], v[222:223]
	s_waitcnt lgkmcnt(2)
	v_mfma_f32_16x16x32_bf16 v[224:227], v[232:235], v[204:207], v[224:227]
	ds_read_b128 v[232:235], v182 offset:45056
	v_pk_add_f32 v[154:155], v[216:217], v[220:221]
	ds_read_b128 v[216:219], v183 offset:63552
	s_waitcnt lgkmcnt(3)
	v_mfma_f32_16x16x32_bf16 v[224:227], v[236:239], v[208:211], v[224:227]
	ds_read_b128 v[236:239], v182 offset:45120
	ds_read_b128 v[220:223], v183 offset:63680
	v_mul_f32_e32 v142, v146, v146
	s_waitcnt lgkmcnt(4)
	v_mfma_f32_16x16x32_bf16 v[224:227], v[240:243], v[212:215], v[224:227]
	ds_read_b128 v[240:243], v183 offset:63488
	v_add_f32_e32 v196, v152, v153
	v_add_f32_e32 v244, v148, v149
	s_waitcnt lgkmcnt(4)
	v_mfma_f32_16x16x32_bf16 v[138:141], v[232:235], v[138:141], 0
	v_mul_f32_e32 v247, v152, v152
	v_mul_f32_e32 v249, v153, v153
	v_mul_f32_e32 v251, v148, v148
	s_waitcnt lgkmcnt(2)
	v_mfma_f32_16x16x32_bf16 v[156:159], v[236:239], v[156:159], v[138:141]
	v_mul_f32_e32 v253, v149, v149
	v_mul_f32_e32 v197, v154, v154
	v_mul_f32_e32 v245, v155, v155
	ds_read_b128 v[138:141], v183 offset:63616
	s_waitcnt lgkmcnt(1)
	v_mfma_f32_16x16x32_bf16 v[200:203], v[240:243], v[200:203], 0
	v_fma_f32 v232, v146, v146, v142
	v_fma_f32 v233, v147, v147, v142
	v_pk_add_f32 v[142:143], v[230:231], v[226:227]
	v_pk_add_f32 v[150:151], v[228:229], v[224:225]
	v_mfma_f32_16x16x32_bf16 v[200:203], v[216:219], v[204:207], v[200:203]
	v_mov_b32_e32 v246, v154
	v_mov_b32_e32 v248, v155
	v_mov_b32_e32 v250, v146
	s_waitcnt lgkmcnt(0)
	v_mfma_f32_16x16x32_bf16 v[138:141], v[138:141], v[208:211], v[200:203]
	v_mov_b32_e32 v252, v147
	v_mul_f32_e32 v205, v150, v150
	v_mul_f32_e32 v207, v151, v151
	v_mfma_f32_16x16x32_bf16 v[200:203], v[220:223], v[212:215], v[138:141]
	v_mul_f32_e32 v209, v142, v142
	v_mul_f32_e32 v211, v143, v143
	v_pk_add_f32 v[212:213], v[246:247], v[248:249]
	v_pk_add_f32 v[214:215], v[250:251], v[252:253]
	v_pk_add_f32 v[196:197], v[196:197], v[244:245]
	s_nop 2
	v_pk_add_f32 v[138:139], v[158:159], v[202:203]
	v_pk_add_f32 v[140:141], v[156:157], v[200:201]
	v_mov_b32_e32 v232, v73
	v_mov_b32_e32 v204, v150
	v_mov_b32_e32 v206, v151
	v_mov_b32_e32 v208, v142
	v_mov_b32_e32 v210, v143
	v_mul_f32_e32 v157, v140, v140
	v_mul_f32_e32 v159, v141, v141
	v_mul_f32_e32 v201, v138, v138
	v_mul_f32_e32 v203, v139, v139
	v_pk_add_f32 v[212:213], v[212:213], v[214:215]
	v_pk_add_f32 v[196:197], v[196:197], v[232:233]
	v_pk_add_f32 v[204:205], v[204:205], v[206:207]
	v_pk_add_f32 v[206:207], v[208:209], v[210:211]
	v_mov_b32_e32 v156, v140
	v_mov_b32_e32 v158, v141
	v_mov_b32_e32 v200, v138
	v_mov_b32_e32 v202, v139
	v_pk_add_f32 v[196:197], v[212:213], v[196:197]
	v_pk_add_f32 v[204:205], v[204:205], v[206:207]
	v_pk_add_f32 v[156:157], v[156:157], v[158:159]
	v_pk_add_f32 v[158:159], v[200:201], v[202:203]
	v_pk_add_f32 v[196:197], v[196:197], v[204:205]
	v_pk_add_f32 v[156:157], v[156:157], v[158:159]
	s_nop 0
	v_pk_add_f32 v[156:157], v[196:197], v[156:157]
	ds_bpermute_b32 v158, v191, v156
	ds_bpermute_b32 v159, v191, v157
	s_waitcnt lgkmcnt(0)
	v_pk_add_f32 v[156:157], v[156:157], v[158:159]
	ds_bpermute_b32 v158, v199, v156
	ds_bpermute_b32 v159, v199, v157
	s_and_saveexec_b64 s[6:7], s[2:3]
	s_cbranch_execz .LBB0_392
	s_waitcnt lgkmcnt(0)
	v_pk_add_f32 v[64:65], v[156:157], v[158:159]
	v_add_u32_e32 v66, s21, v166
	ds_write_b64 v66, v[64:65]
	ds_read_b128 v[68:71], v181 offset:49664
	ds_read_b128 v[64:67], v181 offset:49728
.LBB0_392:
	s_or_b64 exec, exec, s[6:7]
	s_waitcnt lgkmcnt(0)
	ds_read_b128 v[156:159], v187 offset:26624
	ds_read_b128 v[196:199], v181 offset:45056
	ds_read_b128 v[200:203], v187 offset:26688
	ds_read_b128 v[204:207], v181 offset:45120
	ds_read_b128 v[212:215], v187 offset:28928
	ds_read_b128 v[216:219], v187 offset:28992
	s_andn2_b64 vcc, exec, s[4:5]
	s_waitcnt lgkmcnt(4)
	v_mfma_f32_16x16x32_bf16 v[208:211], v[156:159], v[196:199], 0
	s_waitcnt lgkmcnt(1)
	v_mfma_f32_16x16x32_bf16 v[196:199], v[212:215], v[196:199], 0
	v_mfma_f32_16x16x32_bf16 v[208:211], v[200:203], v[204:207], v[208:211]
	s_waitcnt lgkmcnt(0)
	v_mfma_f32_16x16x32_bf16 v[196:199], v[216:219], v[204:207], v[196:199]
	ds_read_b128 v[204:207], v181 offset:47360
	ds_read_b128 v[220:223], v181 offset:47424
	s_nop 3
	v_pk_fma_f32 v[98:99], v[50:51], v[98:99], v[210:211]
	v_pk_fma_f32 v[92:93], v[48:49], v[92:93], v[208:209]
	s_waitcnt lgkmcnt(1)
	v_mfma_f32_16x16x32_bf16 v[224:227], v[156:159], v[204:207], 0
	ds_read_b128 v[208:211], v181 offset:51968
	v_pk_fma_f32 v[112:113], v[54:55], v[112:113], v[198:199]
	v_pk_fma_f32 v[108:109], v[52:53], v[108:109], v[196:197]
	v_mfma_f32_16x16x32_bf16 v[204:207], v[212:215], v[204:207], 0
	s_waitcnt lgkmcnt(1)
	v_mfma_f32_16x16x32_bf16 v[224:227], v[200:203], v[220:223], v[224:227]
	v_mfma_f32_16x16x32_bf16 v[204:207], v[216:219], v[220:223], v[204:207]
	v_mfma_f32_16x16x32_bf16 v[220:223], v[156:159], v[68:71], 0
	s_nop 5
	v_fma_f32 v96, v50, v96, v226
	v_fma_f32 v97, v51, v97, v227
	v_pk_fma_f32 v[94:95], v[48:49], v[94:95], v[224:225]
	v_pk_fma_f32 v[110:111], v[52:53], v[110:111], v[204:205]
	v_mfma_f32_16x16x32_bf16 v[68:71], v[212:215], v[68:71], 0
	v_fma_f32 v116, v54, v116, v206
	v_fma_f32 v117, v55, v117, v207
	v_mfma_f32_16x16x32_bf16 v[220:223], v[200:203], v[64:67], v[220:223]
	v_mfma_f32_16x16x32_bf16 v[64:67], v[216:219], v[64:67], v[68:71]
	s_nop 3
	ds_read_b128 v[68:71], v181 offset:52032
	s_waitcnt lgkmcnt(1)
	v_mfma_f32_16x16x32_bf16 v[156:159], v[156:159], v[208:211], 0
	v_fma_f32 v104, v50, v104, v222
	v_fma_f32 v105, v51, v105, v223
	v_pk_fma_f32 v[100:101], v[48:49], v[100:101], v[220:221]
	v_pk_fma_f32 v[114:115], v[52:53], v[114:115], v[64:65]
	s_waitcnt lgkmcnt(0)
	v_mfma_f32_16x16x32_bf16 v[156:159], v[200:203], v[68:71], v[156:159]
	s_barrier
	v_mfma_f32_16x16x32_bf16 v[196:199], v[212:215], v[208:211], 0
	v_fma_f32 v120, v54, v120, v66
	v_fma_f32 v121, v55, v121, v67
	s_nop 3
	v_pk_fma_f32 v[106:107], v[50:51], v[106:107], v[158:159]
	v_pk_fma_f32 v[102:103], v[48:49], v[102:103], v[156:157]
	v_mfma_f32_16x16x32_bf16 v[48:51], v[216:219], v[68:71], v[196:199]
	s_nop 7
	v_pk_fma_f32 v[118:119], v[52:53], v[118:119], v[48:49]
	v_cvt_pk_bf16_f32 v52, v92, v93
	v_cvt_pk_bf16_f32 v53, v98, v99
	ds_write_b64 v194, v[52:53] offset:63488
	v_cvt_pk_bf16_f32 v52, v94, v95
	v_cvt_pk_bf16_f32 v53, v96, v97
	ds_write_b64 v193, v[52:53] offset:63488
	v_cvt_pk_bf16_f32 v52, v100, v101
	v_cvt_pk_bf16_f32 v53, v104, v105
	ds_write_b64 v192, v[52:53] offset:63488
	v_cvt_pk_bf16_f32 v52, v102, v103
	v_cvt_pk_bf16_f32 v53, v106, v107
	ds_write_b64 v188, v[52:53] offset:63488
	v_cvt_pk_bf16_f32 v52, v108, v109
	v_cvt_pk_bf16_f32 v53, v112, v113
	ds_write_b64 v194, v[52:53] offset:63520
	v_cvt_pk_bf16_f32 v52, v110, v111
	v_cvt_pk_bf16_f32 v53, v116, v117
	v_pk_fma_f32 v[122:123], v[54:55], v[122:123], v[50:51]
	ds_write_b64 v193, v[52:53] offset:63520
	v_cvt_pk_bf16_f32 v52, v114, v115
	v_cvt_pk_bf16_f32 v53, v120, v121
	ds_write_b64 v192, v[52:53] offset:63520
	v_cvt_pk_bf16_f32 v52, v118, v119
	v_cvt_pk_bf16_f32 v53, v122, v123
	ds_write_b64 v188, v[52:53] offset:63520
	ds_read_b128 v[52:55], v166
	ds_read_b128 v[48:51], v167
	s_waitcnt vmcnt(3) lgkmcnt(1)
	v_lshlrev_b32_e32 v54, 16, v145
	v_add_f32_e32 v52, v53, v55
	v_mul_f32_e32 v52, 0x3c000000, v52
	v_max_f32_e32 v52, 0, v52
	v_add_f32_e32 v52, 0x3727c5ac, v52
	v_rsq_f32_e32 v64, v52
	v_lshlrev_b64 v[52:53], 11, v[72:73]
	v_lshl_add_u64 v[66:67], v[88:89], 0, v[52:53]
	v_lshlrev_b32_e32 v52, 16, v144
	v_and_b32_e32 v53, 0xffff0000, v144
	v_and_b32_e32 v55, 0xffff0000, v145
	v_pk_mul_f32 v[52:53], v[152:153], v[52:53]
	v_pk_mul_f32 v[54:55], v[148:149], v[54:55]
	v_pk_mul_f32 v[52:53], v[52:53], v[64:65] op_sel_hi:[1,0]
	v_pk_mul_f32 v[54:55], v[54:55], v[64:65] op_sel_hi:[1,0]
	s_waitcnt lgkmcnt(0)
	v_pk_mul_f32 v[52:53], v[48:49], v[52:53]
	v_pk_mul_f32 v[54:55], v[50:51], v[54:55]
	v_cvt_pk_bf16_f32 v52, v52, v53
	v_cvt_pk_bf16_f32 v53, v54, v55
	global_store_dwordx2 v[66:67], v[52:53], off
	ds_read_b128 v[52:55], v167 offset:64
	s_waitcnt vmcnt(3)
	v_lshlrev_b32_e32 v48, 16, v136
	v_and_b32_e32 v49, 0xffff0000, v136
	v_pk_mul_f32 v[48:49], v[154:155], v[48:49]
	s_nop 0
	v_pk_mul_f32 v[68:69], v[48:49], v[64:65] op_sel_hi:[1,0]
	ds_read_b128 v[48:51], v167 offset:128
	s_waitcnt lgkmcnt(1)
	v_pk_mul_f32 v[52:53], v[52:53], v[68:69]
	v_lshlrev_b32_e32 v68, 16, v137
	v_and_b32_e32 v69, 0xffff0000, v137
	v_pk_mul_f32 v[68:69], v[146:147], v[68:69]
	v_cvt_pk_bf16_f32 v52, v52, v53
	v_pk_mul_f32 v[68:69], v[68:69], v[64:65] op_sel_hi:[1,0]
	s_nop 0
	v_pk_mul_f32 v[54:55], v[54:55], v[68:69]
	s_nop 0
	v_cvt_pk_bf16_f32 v53, v54, v55
	global_store_dwordx2 v[66:67], v[52:53], off offset:32
	s_waitcnt vmcnt(3)
	v_lshlrev_b32_e32 v52, 16, v134
	v_and_b32_e32 v53, 0xffff0000, v134
	v_lshlrev_b32_e32 v54, 16, v135
	v_and_b32_e32 v55, 0xffff0000, v135
	v_pk_mul_f32 v[52:53], v[150:151], v[52:53]
	v_pk_mul_f32 v[54:55], v[142:143], v[54:55]
	v_pk_mul_f32 v[52:53], v[52:53], v[64:65] op_sel_hi:[1,0]
	v_pk_mul_f32 v[54:55], v[54:55], v[64:65] op_sel_hi:[1,0]
	s_waitcnt lgkmcnt(0)
	v_pk_mul_f32 v[52:53], v[48:49], v[52:53]
	v_pk_mul_f32 v[54:55], v[50:51], v[54:55]
	v_cvt_pk_bf16_f32 v52, v52, v53
	v_cvt_pk_bf16_f32 v53, v54, v55
	global_store_dwordx2 v[66:67], v[52:53], off offset:64
	ds_read_b128 v[52:55], v167 offset:192
	s_waitcnt vmcnt(3)
	v_lshlrev_b32_e32 v48, 16, v132
	v_and_b32_e32 v49, 0xffff0000, v132
	v_pk_mul_f32 v[48:49], v[140:141], v[48:49]
	s_nop 0
	v_pk_mul_f32 v[48:49], v[48:49], v[64:65] op_sel_hi:[1,0]
	s_waitcnt lgkmcnt(0)
	v_pk_mul_f32 v[52:53], v[48:49], v[52:53]
	v_lshlrev_b32_e32 v48, 16, v133
	v_and_b32_e32 v49, 0xffff0000, v133
	v_pk_mul_f32 v[48:49], v[138:139], v[48:49]
	v_cvt_pk_bf16_f32 v52, v52, v53
	v_pk_mul_f32 v[48:49], v[48:49], v[64:65] op_sel_hi:[1,0]
	s_nop 0
	v_pk_mul_f32 v[54:55], v[48:49], v[54:55]
	s_nop 0
	v_cvt_pk_bf16_f32 v53, v54, v55
	global_store_dwordx2 v[66:67], v[52:53], off offset:96
	s_cbranch_vccz .LBB0_394
	s_mov_b32 s22, s8
	s_branch .LBB0_377
